# grid barrier: non-leader workgroups poll the top-level generation word directly (skips the per-XCD relay hop)
# speedup vs baseline: 1.0203x; 1.0042x over previous
.LBB0_53:
	s_or_b64 exec, exec, s[8:9]
	v_cvt_f32_u32_e32 v6, v4
	s_waitcnt vmcnt(0)
	v_readfirstlane_b32 s6, v5
	v_sub_u32_e32 v5, 0, v4
	v_rcp_iflag_f32_e32 v6, v6
	v_add_u32_e32 v7, s6, v3
	v_mul_f32_e32 v6, 0x4f7ffffe, v6
	v_cvt_u32_f32_e32 v6, v6
	v_mul_lo_u32 v3, v5, v6
	v_mul_hi_u32 v3, v6, v3
	v_add_u32_e32 v3, v6, v3
	v_mul_hi_u32 v3, v7, v3
	v_mul_lo_u32 v5, v3, v4
	v_sub_u32_e32 v5, v7, v5
	v_add_u32_e32 v6, 1, v3
	v_cmp_ge_u32_e32 vcc, v5, v4
	s_nop 1
	v_cndmask_b32_e32 v3, v3, v6, vcc
	v_sub_u32_e32 v6, v5, v4
	v_cndmask_b32_e32 v5, v5, v6, vcc
	v_add_u32_e32 v6, 1, v3
	v_cmp_ge_u32_e32 vcc, v5, v4
	v_add_u32_e32 v5, 1, v7
	s_nop 0
	v_cndmask_b32_e32 v3, v3, v6, vcc
	v_mul_lo_u32 v6, v4, v3
	v_add_u32_e32 v4, v6, v4
	v_cmp_ne_u32_e32 vcc, v5, v4
	s_and_saveexec_b64 s[6:7], vcc
	s_xor_b64 s[6:7], exec, s[6:7]
	s_cbranch_execz .LBB0_67
	s_movk_i32 s8, 0xd40
	s_mov_b32 s9, 0
	s_lshl_b64 s[8:9], s[8:9], 2
	s_add_u32 s10, s4, s8
	s_addc_u32 s11, s5, s9
	s_waitcnt lgkmcnt(0)
	v_mov_b32_e32 v2, 0
	global_load_dword v4, v2, s[10:11] sc1
	s_waitcnt vmcnt(0)
	v_cmp_eq_u32_e32 vcc, v4, v3
	s_and_saveexec_b64 s[8:9], vcc
	s_cbranch_execz .LBB0_66
	s_mov_b32 s12, 1
	s_mov_b64 s[18:19], 0
	s_branch .LBB0_57

.LBB0_230:
	s_or_b64 exec, exec, s[24:25]
	v_cvt_f32_u32_e32 v6, v4
	s_waitcnt vmcnt(0)
	v_readfirstlane_b32 s8, v5
	v_sub_u32_e32 v5, 0, v4
	v_rcp_iflag_f32_e32 v6, v6
	v_add_u32_e32 v7, s8, v3
	v_mul_f32_e32 v6, 0x4f7ffffe, v6
	v_cvt_u32_f32_e32 v6, v6
	v_mul_lo_u32 v3, v5, v6
	v_mul_hi_u32 v3, v6, v3
	v_add_u32_e32 v3, v6, v3
	v_mul_hi_u32 v3, v7, v3
	v_mul_lo_u32 v5, v3, v4
	v_sub_u32_e32 v5, v7, v5
	v_add_u32_e32 v6, 1, v3
	v_cmp_ge_u32_e32 vcc, v5, v4
	s_nop 1
	v_cndmask_b32_e32 v3, v3, v6, vcc
	v_sub_u32_e32 v6, v5, v4
	v_cndmask_b32_e32 v5, v5, v6, vcc
	v_add_u32_e32 v6, 1, v3
	v_cmp_ge_u32_e32 vcc, v5, v4
	v_add_u32_e32 v5, 1, v7
	s_nop 0
	v_cndmask_b32_e32 v3, v3, v6, vcc
	v_mul_lo_u32 v6, v4, v3
	v_add_u32_e32 v4, v6, v4
	v_cmp_ne_u32_e32 vcc, v5, v4
	s_and_saveexec_b64 s[8:9], vcc
	s_xor_b64 s[8:9], exec, s[8:9]
	s_cbranch_execz .LBB0_244
	s_movk_i32 s14, 0xd40
	s_mov_b32 s15, 0
	s_lshl_b64 s[14:15], s[14:15], 2
	s_add_u32 s26, s6, s14
	s_addc_u32 s27, s7, s15
	s_waitcnt lgkmcnt(0)
	v_mov_b32_e32 v2, 0
	global_load_dword v4, v2, s[26:27] sc1
	s_waitcnt vmcnt(0)
	v_cmp_eq_u32_e32 vcc, v4, v3
	s_and_saveexec_b64 s[24:25], vcc
	s_cbranch_execz .LBB0_243
	s_mov_b32 s13, 1
	s_mov_b64 s[28:29], 0
	s_branch .LBB0_234

.LBB0_348:
	s_or_b64 exec, exec, s[8:9]
	v_cvt_f32_u32_e32 v5, v3
	s_waitcnt vmcnt(0)
	v_readfirstlane_b32 s6, v4
	v_sub_u32_e32 v4, 0, v3
	v_rcp_iflag_f32_e32 v5, v5
	v_add_u32_e32 v6, s6, v2
	v_mul_f32_e32 v5, 0x4f7ffffe, v5
	v_cvt_u32_f32_e32 v5, v5
	v_mul_lo_u32 v2, v4, v5
	v_mul_hi_u32 v2, v5, v2
	v_add_u32_e32 v2, v5, v2
	v_mul_hi_u32 v2, v6, v2
	v_mul_lo_u32 v4, v2, v3
	v_sub_u32_e32 v4, v6, v4
	v_add_u32_e32 v5, 1, v2
	v_cmp_ge_u32_e32 vcc, v4, v3
	s_nop 1
	v_cndmask_b32_e32 v2, v2, v5, vcc
	v_sub_u32_e32 v5, v4, v3
	v_cndmask_b32_e32 v4, v4, v5, vcc
	v_add_u32_e32 v5, 1, v2
	v_cmp_ge_u32_e32 vcc, v4, v3
	v_add_u32_e32 v4, 1, v6
	s_nop 0
	v_cndmask_b32_e32 v2, v2, v5, vcc
	v_mul_lo_u32 v5, v3, v2
	v_add_u32_e32 v3, v5, v3
	v_cmp_ne_u32_e32 vcc, v4, v3
	s_and_saveexec_b64 s[6:7], vcc
	s_xor_b64 s[6:7], exec, s[6:7]
	s_cbranch_execz .LBB0_362
	s_movk_i32 s8, 0xd40
	s_mov_b32 s9, 0
	s_lshl_b64 s[8:9], s[8:9], 2
	s_add_u32 s10, s4, s8
	s_addc_u32 s11, s5, s9
	s_waitcnt lgkmcnt(0)
	v_mov_b32_e32 v1, 0
	global_load_dword v3, v1, s[10:11] sc1
	s_waitcnt vmcnt(0)
	v_cmp_eq_u32_e32 vcc, v3, v2
	s_and_saveexec_b64 s[8:9], vcc
	s_cbranch_execz .LBB0_361
	s_mov_b32 s13, 1
	s_mov_b64 s[20:21], 0
	s_branch .LBB0_352

.LBB0_483:
	s_or_b64 exec, exec, s[8:9]
	v_cvt_f32_u32_e32 v5, v3
	s_waitcnt vmcnt(0)
	v_readfirstlane_b32 s6, v4
	v_sub_u32_e32 v4, 0, v3
	v_rcp_iflag_f32_e32 v5, v5
	v_add_u32_e32 v6, s6, v2
	v_mul_f32_e32 v5, 0x4f7ffffe, v5
	v_cvt_u32_f32_e32 v5, v5
	v_mul_lo_u32 v2, v4, v5
	v_mul_hi_u32 v2, v5, v2
	v_add_u32_e32 v2, v5, v2
	v_mul_hi_u32 v2, v6, v2
	v_mul_lo_u32 v4, v2, v3
	v_sub_u32_e32 v4, v6, v4
	v_add_u32_e32 v5, 1, v2
	v_cmp_ge_u32_e32 vcc, v4, v3
	s_nop 1
	v_cndmask_b32_e32 v2, v2, v5, vcc
	v_sub_u32_e32 v5, v4, v3
	v_cndmask_b32_e32 v4, v4, v5, vcc
	v_add_u32_e32 v5, 1, v2
	v_cmp_ge_u32_e32 vcc, v4, v3
	v_add_u32_e32 v4, 1, v6
	s_nop 0
	v_cndmask_b32_e32 v2, v2, v5, vcc
	v_mul_lo_u32 v5, v3, v2
	v_add_u32_e32 v3, v5, v3
	v_cmp_ne_u32_e32 vcc, v4, v3
	s_and_saveexec_b64 s[6:7], vcc
	s_xor_b64 s[6:7], exec, s[6:7]
	s_cbranch_execz .LBB0_497
	s_movk_i32 s8, 0xd40
	s_mov_b32 s9, 0
	s_lshl_b64 s[8:9], s[8:9], 2
	s_add_u32 s10, s4, s8
	s_addc_u32 s11, s5, s9
	s_waitcnt lgkmcnt(0)
	v_mov_b32_e32 v1, 0
	global_load_dword v3, v1, s[10:11] sc1
	s_waitcnt vmcnt(0)
	v_cmp_eq_u32_e32 vcc, v3, v2
	s_and_saveexec_b64 s[8:9], vcc
	s_cbranch_execz .LBB0_496
	s_mov_b32 s13, 1
	s_mov_b64 s[16:17], 0
	s_branch .LBB0_487

.LBB0_720:
	s_or_b64 exec, exec, s[36:37]
	v_cvt_f32_u32_e32 v10, v4
	s_waitcnt vmcnt(0)
	v_readfirstlane_b32 s8, v5
	v_sub_u32_e32 v5, 0, v4
	v_rcp_iflag_f32_e32 v10, v10
	v_add_u32_e32 v11, s8, v3
	v_mul_f32_e32 v10, 0x4f7ffffe, v10
	v_cvt_u32_f32_e32 v10, v10
	v_mul_lo_u32 v3, v5, v10
	v_mul_hi_u32 v3, v10, v3
	v_add_u32_e32 v3, v10, v3
	v_mul_hi_u32 v3, v11, v3
	v_mul_lo_u32 v5, v3, v4
	v_sub_u32_e32 v5, v11, v5
	v_add_u32_e32 v10, 1, v3
	v_cmp_ge_u32_e32 vcc, v5, v4
	s_nop 1
	v_cndmask_b32_e32 v3, v3, v10, vcc
	v_sub_u32_e32 v10, v5, v4
	v_cndmask_b32_e32 v5, v5, v10, vcc
	v_add_u32_e32 v10, 1, v3
	v_cmp_ge_u32_e32 vcc, v5, v4
	v_add_u32_e32 v5, 1, v11
	s_nop 0
	v_cndmask_b32_e32 v3, v3, v10, vcc
	v_mul_lo_u32 v10, v4, v3
	v_add_u32_e32 v4, v10, v4
	v_cmp_ne_u32_e32 vcc, v5, v4
	s_and_saveexec_b64 s[8:9], vcc
	s_xor_b64 s[8:9], exec, s[8:9]
	s_cbranch_execz .LBB0_734
	s_movk_i32 s26, 0xd40
	s_lshl_b64 s[14:15], s[26:27], 2
	s_add_u32 s38, s6, s14
	s_addc_u32 s39, s7, s15
	s_waitcnt lgkmcnt(0)
	global_load_dword v1, v2, s[38:39] sc1
	s_waitcnt vmcnt(0)
	v_cmp_eq_u32_e32 vcc, v1, v3
	s_and_saveexec_b64 s[36:37], vcc
	s_cbranch_execz .LBB0_733
	s_mov_b32 s13, 1
	s_mov_b64 s[60:61], 0
	s_branch .LBB0_724

.LBB0_775:
	s_or_b64 exec, exec, s[38:39]
	v_cvt_f32_u32_e32 v11, v5
	s_waitcnt vmcnt(0)
	v_readfirstlane_b32 s13, v10
	v_sub_u32_e32 v10, 0, v5
	v_rcp_iflag_f32_e32 v11, v11
	v_add_u32_e32 v12, s13, v3
	v_mul_f32_e32 v11, 0x4f7ffffe, v11
	v_cvt_u32_f32_e32 v11, v11
	v_mul_lo_u32 v3, v10, v11
	v_mul_hi_u32 v3, v11, v3
	v_add_u32_e32 v3, v11, v3
	v_mul_hi_u32 v3, v12, v3
	v_mul_lo_u32 v10, v3, v5
	v_sub_u32_e32 v10, v12, v10
	v_add_u32_e32 v11, 1, v3
	v_cmp_ge_u32_e32 vcc, v10, v5
	s_nop 1
	v_cndmask_b32_e32 v3, v3, v11, vcc
	v_sub_u32_e32 v11, v10, v5
	v_cndmask_b32_e32 v10, v10, v11, vcc
	v_add_u32_e32 v11, 1, v3
	v_cmp_ge_u32_e32 vcc, v10, v5
	v_add_u32_e32 v10, 1, v12
	s_nop 0
	v_cndmask_b32_e32 v3, v3, v11, vcc
	v_mul_lo_u32 v11, v5, v3
	v_add_u32_e32 v5, v11, v5
	v_cmp_ne_u32_e32 vcc, v10, v5
	s_and_saveexec_b64 s[14:15], vcc
	s_xor_b64 s[36:37], exec, s[14:15]
	s_cbranch_execz .LBB0_789
	s_movk_i32 s26, 0xd40
	s_lshl_b64 s[14:15], s[26:27], 2
	s_add_u32 s74, s70, s14
	s_addc_u32 s75, s71, s15
	s_waitcnt lgkmcnt(0)
	global_load_dword v4, v2, s[74:75] sc1
	s_waitcnt vmcnt(0)
	v_cmp_eq_u32_e32 vcc, v4, v3
	s_and_saveexec_b64 s[38:39], vcc
	s_cbranch_execz .LBB0_788
	s_mov_b32 s13, 1
	s_mov_b64 s[76:77], 0
	s_branch .LBB0_779

.LBB0_896:
	s_or_b64 exec, exec, s[8:9]
	v_cvt_f32_u32_e32 v10, v4
	s_waitcnt vmcnt(0)
	v_readfirstlane_b32 s6, v5
	v_sub_u32_e32 v5, 0, v4
	v_rcp_iflag_f32_e32 v10, v10
	v_add_u32_e32 v11, s6, v3
	v_mul_f32_e32 v10, 0x4f7ffffe, v10
	v_cvt_u32_f32_e32 v10, v10
	v_mul_lo_u32 v3, v5, v10
	v_mul_hi_u32 v3, v10, v3
	v_add_u32_e32 v3, v10, v3
	v_mul_hi_u32 v3, v11, v3
	v_mul_lo_u32 v5, v3, v4
	v_sub_u32_e32 v5, v11, v5
	v_add_u32_e32 v10, 1, v3
	v_cmp_ge_u32_e32 vcc, v5, v4
	s_nop 1
	v_cndmask_b32_e32 v3, v3, v10, vcc
	v_sub_u32_e32 v10, v5, v4
	v_cndmask_b32_e32 v5, v5, v10, vcc
	v_add_u32_e32 v10, 1, v3
	v_cmp_ge_u32_e32 vcc, v5, v4
	v_add_u32_e32 v5, 1, v11
	s_nop 0
	v_cndmask_b32_e32 v3, v3, v10, vcc
	v_mul_lo_u32 v10, v4, v3
	v_add_u32_e32 v4, v10, v4
	v_cmp_ne_u32_e32 vcc, v5, v4
	s_and_saveexec_b64 s[6:7], vcc
	s_xor_b64 s[6:7], exec, s[6:7]
	s_cbranch_execz .LBB0_910
	s_movk_i32 s26, 0xd40
	s_lshl_b64 s[8:9], s[26:27], 2
	s_add_u32 s10, s4, s8
	s_addc_u32 s11, s5, s9
	s_waitcnt lgkmcnt(0)
	global_load_dword v1, v2, s[10:11] sc1
	s_waitcnt vmcnt(0)
	v_cmp_eq_u32_e32 vcc, v1, v3
	s_and_saveexec_b64 s[8:9], vcc
	s_cbranch_execz .LBB0_909
	s_mov_b32 s13, 1
	s_mov_b64 s[36:37], 0
	s_branch .LBB0_900
